# v26 + removed 20 redundant compiler lgkmcnt waits and 4 setprio 0/1 toggles inside MFMA blocks, B-fragment LDS bases hoisted out of the loop
# speedup vs baseline: 1.0003x; 1.0003x over previous
; #define PG8_STAGE(bufoff, gbase, voff) do { _Pragma("unroll") for (int _i = 0; _i < 2; ++_i) \
;         pg8_dma16((const char*)(gbase), (voff)[_i], ldsb + (unsigned)((bufoff) + _i * 8192)); } while (0)
; #define PG8_BAR __builtin_amdgcn_s_barrier()
; template <class Epi, class Sched, bool ALIGN_EPI = false, bool SP2 = false>
; __device__ __forceinline__ void gemm_phase(PG8_LAS unsigned char* lds, const Gemm g, const Sched& S, const Epi& E) {
;     int tid_ = threadIdx.x; asm volatile("" : "+v"(tid_)); const int tid = tid_, wid = __builtin_amdgcn_readfirstlane(tid >> 6), lane = tid & 63, wr = wid >> 2, wc = wid & 3, fr = lane & 15, fq = lane >> 4;
;     const int K = g.K, nt = K / BK;
;     unsigned voffA[2], voffB[2];
; #pragma unroll
;     for (int i = 0; i < 2; ++i) { int R, C; stage_rc(tid * 16 + i * 8192, R, C); const int Rb = Epi::PERM ? ((R & ~31) + perm32(R & 31)) : R;
;         voffA[i] = (unsigned)(R * K + C) * 2u; voffB[i] = (unsigned)(Rb * K + C) * 2u; }
;     const size_t kstep = (size_t)(BK * 2);
;     const size_t hstep = (size_t)HALF * K * 2;
;     const size_t tstep = 2 * hstep;
;     const unsigned ldsw = (unsigned)wid * 1024u;
;     const unsigned ldsb = (unsigned)__builtin_amdgcn_readfirstlane((int)((unsigned)(size_t)lds + ldsw));
;     const int aoff = lds_byte(wr * 64 + fr, fq * 8), boff = lds_byte(wc * 32 + fr, fq * 8);
;     ...
;     Unit cur, nxt; int ui = 0;
;     if (!S.next(0, cur)) return;
;     f32x4 acc[2][2][4][2];
; #pragma unroll
;     for (int a = 0; a < 2; ++a)
; #pragma unroll
;         for (int b = 0; b < 2; ++b)
; #pragma unroll
;             for (int m = 0; m < 4; ++m)
; #pragma unroll
;                 for (int n = 0; n < 2; ++n) acc[a][b][m][n] = (f32x4){0.f, 0.f, 0.f, 0.f};
;     bf16x8 At[4][2], B0[2][2], B1[2][2];
;     const char* cA = (const char*)g.A + (size_t)cur.pm * tstep; const char* cB = (const char*)g.Bt + (size_t)cur.pn * tstep;
;     S.a_ready(cur);
;     if constexpr (SP2) {
;         PG8_STAGE(PG8_SB(0, 0), cB, voffB); PG8_STAGE(PG8_SB(0, 1), cB + hstep, voffB); PG8_STAGE(PG8_SA(0, 0), cA, voffA); PG8_STAGE(PG8_SA(0, 1), cA + hstep, voffA);
;         if (wr == 1) PG8_BAR;
;         PG8_WAIT_V(2); PG8_BAR;
;         PG8_STAGE(PG8_SB(1, 0), cB + kstep, voffB); PG8_STAGE(PG8_SA(1, 0), cA + kstep, voffA); PG8_STAGE(PG8_SB(1, 1), cB + hstep + kstep, voffB);
;         PG8_WAIT_V(6); PG8_BAR;
.LBB0_295:
	v_bfe_u32 v1, v0, 4, 2
	v_and_b32_e32 v0, 15, v0
	v_lshlrev_b32_e32 v3, 4, v1
	v_lshlrev_b32_e32 v5, 2, v0
	s_and_b32 s66, s5, 3
	v_lshl_or_b32 v4, v0, 6, v3
	s_lshl_b32 s5, s8, 13
	v_and_b32_e32 v6, 32, v5
	s_lshr_b32 s60, s21, 6
	v_bitop3_b32 v7, v4, s5, v6 bitop3:0xde
	s_lshl_b32 s5, s66, 12
	s_add_u32 s6, s12, 0x80
	v_bitop3_b32 v4, v4, s5, v6 bitop3:0xde
	s_waitcnt vmcnt(2)
	s_barrier
	s_addc_u32 s7, s13, 0
	s_add_i32 s67, s49, 0x18000
	s_mov_b32 s5, m0
	s_mov_b32 m0, s67
	s_nop 0
	global_load_lds_dwordx4 v151, s[6:7]
	s_mov_b32 m0, s5
	s_add_i32 s70, s49, 0x1a000
	s_mov_b32 s5, m0
	s_mov_b32 m0, s70
	s_nop 0
	global_load_lds_dwordx4 v199, s[6:7]
	s_mov_b32 m0, s5
	s_add_u32 s6, s36, 0x80
	s_addc_u32 s7, s37, 0
	s_add_i32 s71, s49, 0x8000
	s_mov_b32 s5, m0
	s_mov_b32 m0, s71
	s_nop 0
	global_load_lds_dwordx4 v148, s[6:7]
	s_mov_b32 m0, s5
	s_add_i32 s74, s49, 0xa000
	s_mov_b32 s5, m0
	s_mov_b32 m0, s74
	s_nop 0
	global_load_lds_dwordx4 v198, s[6:7]
	s_mov_b32 m0, s5
	s_add_u32 s0, s0, 0x80
	s_addc_u32 s1, s1, 0
	s_add_i32 s75, s49, 0x1c000
	s_mov_b32 s5, m0
	s_mov_b32 m0, s75
	s_nop 0
	global_load_lds_dwordx4 v151, s[0:1]
	s_mov_b32 m0, s5
	s_add_i32 s76, s49, 0x1e000
	s_add_i32 s77, s60, -2
	s_add_i32 s78, s49, 0xc000
	s_mov_b32 s5, m0
	s_mov_b32 m0, s76
	s_nop 0
	global_load_lds_dwordx4 v199, s[0:1]
	s_mov_b32 m0, s5
	s_cmpk_lt_u32 s4, 0x100
	s_cselect_b64 s[24:25], -1, 0
	s_and_b32 s4, s4, 0xffffff00
	s_lshl_b32 s5, s66, 6
	s_or_b32 s4, s5, s4
	s_add_i32 s80, s49, 0xe000
	s_lshl_b32 s81, s59, 4
	s_lshl_b32 s82, s59, 3
	s_cmp_eq_u64 s[16:17], 0
	s_cselect_b64 s[26:27], -1, 0
	s_cmp_lg_u64 s[16:17], 0
	s_cselect_b64 s[28:29], -1, 0
	s_abs_i32 s83, s82
	v_lshlrev_b32_e32 v2, 3, v1
	v_cmp_eq_u32_e64 s[0:1], 0, v1
	v_cvt_f32_u32_e32 v1, s83
	v_or3_b32 v201, s4, v3, v0
	s_movk_i32 s4, 0x100
	v_cmp_gt_i32_e64 s[4:5], s4, v201
	v_rcp_iflag_f32_e32 v1, v1
	v_lshl_or_b32 v200, s8, 6, v0
	v_writelane_b32 v226, s4, 35
	v_lshlrev_b32_e32 v0, 2, v201
	v_add_u32_e32 v204, s46, v0
	v_writelane_b32 v226, s5, 36
	v_cmp_eq_u32_e64 s[4:5], 0, v201
	s_waitcnt vmcnt(6)
	s_mov_b32 s79, 0
	s_mov_b32 s21, s57
	v_writelane_b32 v226, s4, 33
	v_lshl_or_b32 v206, s66, 5, v2
	s_bfe_i32 s59, s59, 0x1001c
	v_writelane_b32 v226, s5, 34
	s_lshl_b32 s4, s8, 8
	v_readlane_b32 s5, v226, 41
	v_add_u32_e32 v207, 0, v4
	v_add_u32_e32 v229, 0x10000, v207
	v_add_u32_e32 v230, 0x14000, v207
	v_add_u32_e32 v231, 0x18000, v207
	v_add_u32_e32 v232, 0x1c000, v207
	v_add_u32_e32 v208, 0, v7
	v_add_u32_e32 v202, s5, v0
	v_mul_f32_e32 v0, 0x4f7ffffe, v1
	v_cvt_u32_f32_e32 v0, v0
	s_add_i32 s5, s5, s4
	s_add_i32 s4, s46, s4
	v_add_u32_e32 v203, s5, v5
	v_add_u32_e32 v205, s4, v5
	s_sub_i32 s4, 0, s83
	v_readfirstlane_b32 s5, v0
	s_mul_i32 s4, s4, s5
	s_mul_hi_u32 s4, s5, s4
	s_add_i32 s84, s5, s4
	v_readlane_b32 s7, v226, 20
	s_barrier
	s_branch .LBB0_298

; #define PG8_STAGE(bufoff, gbase, voff) do { _Pragma("unroll") for (int _i = 0; _i < 2; ++_i) \
;         pg8_dma16((const char*)(gbase), (voff)[_i], ldsb + (unsigned)((bufoff) + _i * 8192)); } while (0)
; #define PG8_LDA(dst, b, h) do { _Pragma("unroll") for (int m = 0; m < 4; ++m) _Pragma("unroll") for (int k = 0; k < 2; ++k) dst[m][k] = *(const PG8_LAS bf16x8*)(lds + PG8_SA(b, h) + aoff + m * 2048 + k * 1024); } while (0)
; #define PG8_LDB(dst, b, h) do { _Pragma("unroll") for (int n = 0; n < 2; ++n) _Pragma("unroll") for (int k = 0; k < 2; ++k) dst[n][k] = *(const PG8_LAS bf16x8*)(lds + PG8_SB(b, h) + boff + n * 2048 + k * 1024); } while (0)
; #define PG8_MMA(ai, bj, At, Bt) do { __builtin_amdgcn_s_setprio(1); _Pragma("unroll") for (int m = 0; m < 4; ++m) _Pragma("unroll") for (int n = 0; n < 2; ++n) _Pragma("unroll") for (int k = 0; k < 2; ++k) \
;         acc[ai][bj][m][n] = __builtin_amdgcn_mfma_f32_16x16x32_bf16(Bt[n][k], At[m][k], acc[ai][bj][m][n], 0, 0, 0); __builtin_amdgcn_s_setprio(0); } while (0)
; #define PG8_WAIT_V(n) asm volatile("s_waitcnt vmcnt(" #n ")" ::: "memory")
; #define PG8_WAIT_L(n) asm volatile("s_waitcnt lgkmcnt(" #n ")" ::: "memory")
; #define PG8_BAR __builtin_amdgcn_s_barrier()
; #define PG8_SCHED __builtin_amdgcn_sched_barrier(0)
; template <class Epi, class Sched, bool ALIGN_EPI = false, bool SP2 = false>
; __device__ __forceinline__ void gemm_phase(PG8_LAS unsigned char* lds, const Gemm g, const Sched& S, const Epi& E) {
;     ...
;             PG8_LDB(B0, 0, 0); PG8_LDB(B1, 0, 1); PG8_SCHED; PG8_LDA(At, 0, 0); PG8_STAGE(PG8_SA(1, 1), a1 + hstep, voffA);
;             PG8_WAIT_V(8); PG8_WAIT_L(0); PG8_BAR; PG8_MMA(0, 0, At, B0); PG8_MMA(0, 1, At, B1); PG8_BAR; PG8_SCHED;
;             PG8_LDA(At, 0, 1); PG8_STAGE(PG8_SB(0, 0), b2, voffB); PG8_STAGE(PG8_SB(0, 1), b2 + hstep, voffB); PG8_STAGE(PG8_SA(0, 0), a2, voffA);
;             PG8_WAIT_V(8); PG8_WAIT_L(0); PG8_BAR; PG8_MMA(1, 0, At, B0); PG8_MMA(1, 1, At, B1); PG8_BAR; PG8_SCHED;
;             PG8_LDB(B0, 1, 0); PG8_LDB(B1, 1, 1); PG8_SCHED; PG8_LDA(At, 1, 0); PG8_STAGE(PG8_SA(0, 1), a2 + hstep, voffA);
;             PG8_WAIT_V(8); PG8_WAIT_L(0); PG8_BAR; PG8_MMA(0, 0, At, B0); PG8_MMA(0, 1, At, B1); PG8_BAR; PG8_SCHED;
.LBB0_305:
	ds_read_b128 v[128:131], v229
	ds_read_b128 v[132:135], v229 offset:1024
	ds_read_b128 v[136:139], v229 offset:2048
	ds_read_b128 v[140:143], v229 offset:3072
	ds_read_b128 v[144:147], v230
	ds_read_b128 v[152:155], v230 offset:1024
	ds_read_b128 v[156:159], v230 offset:2048
	ds_read_b128 v[160:163], v230 offset:3072
	s_add_i32 s58, s12, 2
	s_cmp_eq_u32 s77, s12
	s_cselect_b32 s40, s30, s72
	s_cselect_b32 s41, s31, s95
	s_cselect_b32 s36, s34, vcc_lo
	s_cselect_b32 s37, s35, vcc_hi
	s_add_u32 s12, s40, 0x80
	s_addc_u32 s13, s41, 0
	ds_read_b128 v[164:167], v208
	ds_read_b128 v[168:171], v208 offset:1024
	ds_read_b128 v[172:175], v208 offset:2048
	ds_read_b128 v[176:179], v208 offset:3072
	ds_read_b128 v[180:183], v208 offset:4096
	ds_read_b128 v[210:213], v208 offset:5120
	ds_read_b128 v[214:217], v208 offset:6144
	ds_read_b128 v[218:221], v208 offset:7168
	s_mov_b32 m0, s78
	s_nop 0
	global_load_lds_dwordx4 v148, s[10:11]
	s_mov_b32 m0, s80
	s_nop 0
	global_load_lds_dwordx4 v198, s[10:11]
	s_waitcnt vmcnt(8)
	s_waitcnt lgkmcnt(0)
	s_barrier
	s_setprio 1
	v_mfma_f32_16x16x32_bf16 v[124:127], v[128:131], v[164:167], v[124:127]
	v_mfma_f32_16x16x32_bf16 v[116:119], v[136:139], v[164:167], v[116:119]
	v_mfma_f32_16x16x32_bf16 v[108:111], v[128:131], v[172:175], v[108:111]
	v_mfma_f32_16x16x32_bf16 v[100:103], v[136:139], v[172:175], v[100:103]
	v_mfma_f32_16x16x32_bf16 v[92:95], v[128:131], v[180:183], v[92:95]
	v_mfma_f32_16x16x32_bf16 v[84:87], v[136:139], v[180:183], v[84:87]
	v_mfma_f32_16x16x32_bf16 v[76:79], v[128:131], v[214:217], v[76:79]
	v_mfma_f32_16x16x32_bf16 v[68:71], v[136:139], v[214:217], v[68:71]
	v_mfma_f32_16x16x32_bf16 v[124:127], v[132:135], v[168:171], v[124:127]
	v_mfma_f32_16x16x32_bf16 v[116:119], v[140:143], v[168:171], v[116:119]
	v_mfma_f32_16x16x32_bf16 v[108:111], v[132:135], v[176:179], v[108:111]
	v_mfma_f32_16x16x32_bf16 v[100:103], v[140:143], v[176:179], v[100:103]
	v_mfma_f32_16x16x32_bf16 v[92:95], v[132:135], v[210:213], v[92:95]
	v_mfma_f32_16x16x32_bf16 v[84:87], v[140:143], v[210:213], v[84:87]
	v_mfma_f32_16x16x32_bf16 v[76:79], v[132:135], v[218:221], v[76:79]
	v_mfma_f32_16x16x32_bf16 v[68:71], v[140:143], v[218:221], v[68:71]
	v_mfma_f32_16x16x32_bf16 v[120:123], v[144:147], v[164:167], v[120:123]
	v_mfma_f32_16x16x32_bf16 v[112:115], v[156:159], v[164:167], v[112:115]
	v_mfma_f32_16x16x32_bf16 v[104:107], v[144:147], v[172:175], v[104:107]
	v_mfma_f32_16x16x32_bf16 v[96:99], v[156:159], v[172:175], v[96:99]
	v_mfma_f32_16x16x32_bf16 v[88:91], v[144:147], v[180:183], v[88:91]
	v_mfma_f32_16x16x32_bf16 v[80:83], v[156:159], v[180:183], v[80:83]
	v_mfma_f32_16x16x32_bf16 v[72:75], v[144:147], v[214:217], v[72:75]
	v_mfma_f32_16x16x32_bf16 v[64:67], v[156:159], v[214:217], v[64:67]
	v_mfma_f32_16x16x32_bf16 v[120:123], v[152:155], v[168:171], v[120:123]
	v_mfma_f32_16x16x32_bf16 v[112:115], v[160:163], v[168:171], v[112:115]
	v_mfma_f32_16x16x32_bf16 v[104:107], v[152:155], v[176:179], v[104:107]
	v_mfma_f32_16x16x32_bf16 v[96:99], v[160:163], v[176:179], v[96:99]
	v_mfma_f32_16x16x32_bf16 v[88:91], v[152:155], v[210:213], v[88:91]
	v_mfma_f32_16x16x32_bf16 v[80:83], v[160:163], v[210:213], v[80:83]
	v_mfma_f32_16x16x32_bf16 v[72:75], v[152:155], v[218:221], v[72:75]
	v_mfma_f32_16x16x32_bf16 v[64:67], v[160:163], v[218:221], v[64:67]
	s_setprio 0
	s_barrier
	ds_read_b128 v[164:167], v208 offset:16384
	ds_read_b128 v[168:171], v208 offset:17408
	ds_read_b128 v[172:175], v208 offset:18432
	ds_read_b128 v[176:179], v208 offset:19456
	ds_read_b128 v[180:183], v208 offset:20480
	ds_read_b128 v[210:213], v208 offset:21504
	ds_read_b128 v[214:217], v208 offset:22528
	ds_read_b128 v[218:221], v208 offset:23552
	s_mov_b32 m0, s50
	s_nop 0
	global_load_lds_dwordx4 v151, s[36:37]
	s_mov_b32 m0, s51
	s_nop 0
	global_load_lds_dwordx4 v199, s[36:37]
	s_add_u32 s4, s36, s47
	s_addc_u32 s5, s37, 0
	s_mov_b32 m0, s61
	s_nop 0
	global_load_lds_dwordx4 v151, s[4:5]
	s_mov_b32 m0, s62
	s_nop 0
	global_load_lds_dwordx4 v199, s[4:5]
	s_mov_b32 m0, s49
	s_nop 0
	global_load_lds_dwordx4 v148, s[40:41]
	s_mov_b32 m0, s63
	s_nop 0
	global_load_lds_dwordx4 v198, s[40:41]
	s_waitcnt vmcnt(8)
	s_waitcnt lgkmcnt(0)
	s_barrier
	s_setprio 1
	v_mfma_f32_16x16x32_bf16 v[60:63], v[128:131], v[164:167], v[60:63]
	v_mfma_f32_16x16x32_bf16 v[52:55], v[136:139], v[164:167], v[52:55]
	v_mfma_f32_16x16x32_bf16 v[44:47], v[128:131], v[172:175], v[44:47]
	v_mfma_f32_16x16x32_bf16 v[36:39], v[136:139], v[172:175], v[36:39]
	v_mfma_f32_16x16x32_bf16 v[28:31], v[128:131], v[180:183], v[28:31]
	v_mfma_f32_16x16x32_bf16 v[20:23], v[136:139], v[180:183], v[20:23]
	v_mfma_f32_16x16x32_bf16 v[12:15], v[128:131], v[214:217], v[12:15]
	v_mfma_f32_16x16x32_bf16 v[4:7], v[136:139], v[214:217], v[4:7]
	v_mfma_f32_16x16x32_bf16 v[60:63], v[132:135], v[168:171], v[60:63]
	v_mfma_f32_16x16x32_bf16 v[52:55], v[140:143], v[168:171], v[52:55]
	v_mfma_f32_16x16x32_bf16 v[44:47], v[132:135], v[176:179], v[44:47]
	v_mfma_f32_16x16x32_bf16 v[36:39], v[140:143], v[176:179], v[36:39]
	v_mfma_f32_16x16x32_bf16 v[28:31], v[132:135], v[210:213], v[28:31]
	v_mfma_f32_16x16x32_bf16 v[20:23], v[140:143], v[210:213], v[20:23]
	v_mfma_f32_16x16x32_bf16 v[12:15], v[132:135], v[218:221], v[12:15]
	v_mfma_f32_16x16x32_bf16 v[4:7], v[140:143], v[218:221], v[4:7]
	v_mfma_f32_16x16x32_bf16 v[56:59], v[144:147], v[164:167], v[56:59]
	v_mfma_f32_16x16x32_bf16 v[48:51], v[156:159], v[164:167], v[48:51]
	v_mfma_f32_16x16x32_bf16 v[40:43], v[144:147], v[172:175], v[40:43]
	v_mfma_f32_16x16x32_bf16 v[32:35], v[156:159], v[172:175], v[32:35]
	v_mfma_f32_16x16x32_bf16 v[24:27], v[144:147], v[180:183], v[24:27]
	v_mfma_f32_16x16x32_bf16 v[16:19], v[156:159], v[180:183], v[16:19]
	v_mfma_f32_16x16x32_bf16 v[8:11], v[144:147], v[214:217], v[8:11]
	v_mfma_f32_16x16x32_bf16 v[0:3], v[156:159], v[214:217], v[0:3]
	v_mfma_f32_16x16x32_bf16 v[56:59], v[152:155], v[168:171], v[56:59]
	v_mfma_f32_16x16x32_bf16 v[48:51], v[160:163], v[168:171], v[48:51]
	v_mfma_f32_16x16x32_bf16 v[40:43], v[152:155], v[176:179], v[40:43]
	v_mfma_f32_16x16x32_bf16 v[32:35], v[160:163], v[176:179], v[32:35]
	v_mfma_f32_16x16x32_bf16 v[24:27], v[152:155], v[210:213], v[24:27]
	v_mfma_f32_16x16x32_bf16 v[16:19], v[160:163], v[210:213], v[16:19]
	v_mfma_f32_16x16x32_bf16 v[8:11], v[152:155], v[218:221], v[8:11]
	v_mfma_f32_16x16x32_bf16 v[0:3], v[160:163], v[218:221], v[0:3]
	s_setprio 0
	s_barrier
; #define PG8_STAGE(bufoff, gbase, voff) do { _Pragma("unroll") for (int _i = 0; _i < 2; ++_i) \
;         pg8_dma16((const char*)(gbase), (voff)[_i], ldsb + (unsigned)((bufoff) + _i * 8192)); } while (0)
; #define PG8_LDA(dst, b, h) do { _Pragma("unroll") for (int m = 0; m < 4; ++m) _Pragma("unroll") for (int k = 0; k < 2; ++k) dst[m][k] = *(const PG8_LAS bf16x8*)(lds + PG8_SA(b, h) + aoff + m * 2048 + k * 1024); } while (0)
; #define PG8_LDB(dst, b, h) do { _Pragma("unroll") for (int n = 0; n < 2; ++n) _Pragma("unroll") for (int k = 0; k < 2; ++k) dst[n][k] = *(const PG8_LAS bf16x8*)(lds + PG8_SB(b, h) + boff + n * 2048 + k * 1024); } while (0)
; #define PG8_MMA(ai, bj, At, Bt) do { __builtin_amdgcn_s_setprio(1); _Pragma("unroll") for (int m = 0; m < 4; ++m) _Pragma("unroll") for (int n = 0; n < 2; ++n) _Pragma("unroll") for (int k = 0; k < 2; ++k) \
;         acc[ai][bj][m][n] = __builtin_amdgcn_mfma_f32_16x16x32_bf16(Bt[n][k], At[m][k], acc[ai][bj][m][n], 0, 0, 0); __builtin_amdgcn_s_setprio(0); } while (0)
; #define PG8_WAIT_V(n) asm volatile("s_waitcnt vmcnt(" #n ")" ::: "memory")
; #define PG8_WAIT_L(n) asm volatile("s_waitcnt lgkmcnt(" #n ")" ::: "memory")
; #define PG8_BAR __builtin_amdgcn_s_barrier()
; #define PG8_SCHED __builtin_amdgcn_sched_barrier(0)
; template <class Epi, class Sched, bool ALIGN_EPI = false, bool SP2 = false>
; __device__ __forceinline__ void gemm_phase(PG8_LAS unsigned char* lds, const Gemm g, const Sched& S, const Epi& E) {
;     ...
;             PG8_LDB(B0, 1, 0); PG8_LDB(B1, 1, 1); PG8_SCHED; PG8_LDA(At, 1, 0); PG8_STAGE(PG8_SA(0, 1), a2 + hstep, voffA);
;             PG8_WAIT_V(8); PG8_WAIT_L(0); PG8_BAR; PG8_MMA(0, 0, At, B0); PG8_MMA(0, 1, At, B1); PG8_BAR; PG8_SCHED;
;             PG8_LDA(At, 1, 1); PG8_STAGE(PG8_SB(1, 0), b3, voffB); PG8_STAGE(PG8_SB(1, 1), b3 + hstep, voffB); PG8_STAGE(PG8_SA(1, 0), a3, voffA);
;             PG8_WAIT_V(8); PG8_WAIT_L(0); PG8_BAR; PG8_MMA(1, 0, At, B0); PG8_MMA(1, 1, At, B1); PG8_BAR; PG8_SCHED;
	ds_read_b128 v[128:131], v231
	ds_read_b128 v[132:135], v231 offset:1024
	ds_read_b128 v[136:139], v231 offset:2048
	ds_read_b128 v[140:143], v231 offset:3072
	ds_read_b128 v[144:147], v232
	ds_read_b128 v[152:155], v232 offset:1024
	ds_read_b128 v[156:159], v232 offset:2048
	ds_read_b128 v[160:163], v232 offset:3072
	ds_read_b128 v[164:167], v208 offset:32768
	ds_read_b128 v[168:171], v208 offset:33792
	ds_read_b128 v[172:175], v208 offset:34816
	ds_read_b128 v[176:179], v208 offset:35840
	ds_read_b128 v[180:183], v208 offset:36864
	ds_read_b128 v[210:213], v208 offset:37888
	ds_read_b128 v[214:217], v208 offset:38912
	ds_read_b128 v[218:221], v208 offset:39936
	s_add_u32 s4, s40, s47
	s_addc_u32 s5, s41, 0
	s_mov_b32 m0, s64
	s_nop 0
	global_load_lds_dwordx4 v148, s[4:5]
	s_mov_b32 m0, s65
	s_nop 0
	global_load_lds_dwordx4 v198, s[4:5]
	s_waitcnt vmcnt(8)
	s_waitcnt lgkmcnt(0)
	s_barrier
	s_setprio 1
	v_mfma_f32_16x16x32_bf16 v[124:127], v[128:131], v[164:167], v[124:127]
	v_mfma_f32_16x16x32_bf16 v[116:119], v[136:139], v[164:167], v[116:119]
	v_mfma_f32_16x16x32_bf16 v[108:111], v[128:131], v[172:175], v[108:111]
	v_mfma_f32_16x16x32_bf16 v[100:103], v[136:139], v[172:175], v[100:103]
	v_mfma_f32_16x16x32_bf16 v[92:95], v[128:131], v[180:183], v[92:95]
	v_mfma_f32_16x16x32_bf16 v[84:87], v[136:139], v[180:183], v[84:87]
	v_mfma_f32_16x16x32_bf16 v[76:79], v[128:131], v[214:217], v[76:79]
	v_mfma_f32_16x16x32_bf16 v[68:71], v[136:139], v[214:217], v[68:71]
	v_mfma_f32_16x16x32_bf16 v[124:127], v[132:135], v[168:171], v[124:127]
	v_mfma_f32_16x16x32_bf16 v[116:119], v[140:143], v[168:171], v[116:119]
	v_mfma_f32_16x16x32_bf16 v[108:111], v[132:135], v[176:179], v[108:111]
	v_mfma_f32_16x16x32_bf16 v[100:103], v[140:143], v[176:179], v[100:103]
	v_mfma_f32_16x16x32_bf16 v[92:95], v[132:135], v[210:213], v[92:95]
	v_mfma_f32_16x16x32_bf16 v[84:87], v[140:143], v[210:213], v[84:87]
	v_mfma_f32_16x16x32_bf16 v[76:79], v[132:135], v[218:221], v[76:79]
	v_mfma_f32_16x16x32_bf16 v[68:71], v[140:143], v[218:221], v[68:71]
	v_mfma_f32_16x16x32_bf16 v[120:123], v[144:147], v[164:167], v[120:123]
	v_mfma_f32_16x16x32_bf16 v[112:115], v[156:159], v[164:167], v[112:115]
	v_mfma_f32_16x16x32_bf16 v[104:107], v[144:147], v[172:175], v[104:107]
	v_mfma_f32_16x16x32_bf16 v[96:99], v[156:159], v[172:175], v[96:99]
	v_mfma_f32_16x16x32_bf16 v[88:91], v[144:147], v[180:183], v[88:91]
	v_mfma_f32_16x16x32_bf16 v[80:83], v[156:159], v[180:183], v[80:83]
	v_mfma_f32_16x16x32_bf16 v[72:75], v[144:147], v[214:217], v[72:75]
	v_mfma_f32_16x16x32_bf16 v[64:67], v[156:159], v[214:217], v[64:67]
	v_mfma_f32_16x16x32_bf16 v[120:123], v[152:155], v[168:171], v[120:123]
	v_mfma_f32_16x16x32_bf16 v[112:115], v[160:163], v[168:171], v[112:115]
	v_mfma_f32_16x16x32_bf16 v[104:107], v[152:155], v[176:179], v[104:107]
	v_mfma_f32_16x16x32_bf16 v[96:99], v[160:163], v[176:179], v[96:99]
	v_mfma_f32_16x16x32_bf16 v[88:91], v[152:155], v[210:213], v[88:91]
	v_mfma_f32_16x16x32_bf16 v[80:83], v[160:163], v[210:213], v[80:83]
	v_mfma_f32_16x16x32_bf16 v[72:75], v[152:155], v[218:221], v[72:75]
	v_mfma_f32_16x16x32_bf16 v[64:67], v[160:163], v[218:221], v[64:67]
	s_setprio 0
	s_barrier
	ds_read_b128 v[164:167], v208 offset:49152
	ds_read_b128 v[168:171], v208 offset:50176
	ds_read_b128 v[172:175], v208 offset:51200
	ds_read_b128 v[176:179], v208 offset:52224
	ds_read_b128 v[180:183], v208 offset:53248
	ds_read_b128 v[210:213], v208 offset:54272
	ds_read_b128 v[214:217], v208 offset:55296
	ds_read_b128 v[218:221], v208 offset:56320
	s_add_u32 s4, s36, 0x80
	s_addc_u32 s5, s37, 0
	s_mov_b32 m0, s67
	s_nop 0
	global_load_lds_dwordx4 v151, s[4:5]
	s_mov_b32 m0, s70
	s_nop 0
	global_load_lds_dwordx4 v199, s[4:5]
	s_add_u32 s4, s4, s47
	s_addc_u32 s5, s5, 0
	s_mov_b32 m0, s75
	s_nop 0
	global_load_lds_dwordx4 v151, s[4:5]
	s_mov_b32 m0, s76
	s_nop 0
	global_load_lds_dwordx4 v199, s[4:5]
	s_mov_b32 m0, s71
	s_nop 0
	global_load_lds_dwordx4 v148, s[12:13]
	s_mov_b32 m0, s74
	s_nop 0
	global_load_lds_dwordx4 v198, s[12:13]
	s_add_u32 s72, s72, 0x100
	s_addc_u32 s95, s95, 0
	s_add_u32 vcc_lo, vcc_lo, 0x100
	s_addc_u32 vcc_hi, vcc_hi, 0
	s_add_u32 s10, s10, 0x100
	s_addc_u32 s11, s11, 0
	s_mov_b32 s12, s58
	s_cmp_ge_u32 s58, s60
	s_waitcnt vmcnt(8)
	s_waitcnt lgkmcnt(0)
	s_barrier
	s_setprio 1
	v_mfma_f32_16x16x32_bf16 v[60:63], v[128:131], v[164:167], v[60:63]
	v_mfma_f32_16x16x32_bf16 v[52:55], v[136:139], v[164:167], v[52:55]
	v_mfma_f32_16x16x32_bf16 v[44:47], v[128:131], v[172:175], v[44:47]
	v_mfma_f32_16x16x32_bf16 v[36:39], v[136:139], v[172:175], v[36:39]
	v_mfma_f32_16x16x32_bf16 v[28:31], v[128:131], v[180:183], v[28:31]
	v_mfma_f32_16x16x32_bf16 v[20:23], v[136:139], v[180:183], v[20:23]
	v_mfma_f32_16x16x32_bf16 v[12:15], v[128:131], v[214:217], v[12:15]
	v_mfma_f32_16x16x32_bf16 v[4:7], v[136:139], v[214:217], v[4:7]
	v_mfma_f32_16x16x32_bf16 v[60:63], v[132:135], v[168:171], v[60:63]
	v_mfma_f32_16x16x32_bf16 v[52:55], v[140:143], v[168:171], v[52:55]
	v_mfma_f32_16x16x32_bf16 v[44:47], v[132:135], v[176:179], v[44:47]
	v_mfma_f32_16x16x32_bf16 v[36:39], v[140:143], v[176:179], v[36:39]
	v_mfma_f32_16x16x32_bf16 v[28:31], v[132:135], v[210:213], v[28:31]
	v_mfma_f32_16x16x32_bf16 v[20:23], v[140:143], v[210:213], v[20:23]
	v_mfma_f32_16x16x32_bf16 v[12:15], v[132:135], v[218:221], v[12:15]
	v_mfma_f32_16x16x32_bf16 v[4:7], v[140:143], v[218:221], v[4:7]
	v_mfma_f32_16x16x32_bf16 v[56:59], v[144:147], v[164:167], v[56:59]
	v_mfma_f32_16x16x32_bf16 v[48:51], v[156:159], v[164:167], v[48:51]
	v_mfma_f32_16x16x32_bf16 v[40:43], v[144:147], v[172:175], v[40:43]
	v_mfma_f32_16x16x32_bf16 v[32:35], v[156:159], v[172:175], v[32:35]
	v_mfma_f32_16x16x32_bf16 v[24:27], v[144:147], v[180:183], v[24:27]
	v_mfma_f32_16x16x32_bf16 v[16:19], v[156:159], v[180:183], v[16:19]
	v_mfma_f32_16x16x32_bf16 v[8:11], v[144:147], v[214:217], v[8:11]
	v_mfma_f32_16x16x32_bf16 v[0:3], v[156:159], v[214:217], v[0:3]
	v_mfma_f32_16x16x32_bf16 v[56:59], v[152:155], v[168:171], v[56:59]
	v_mfma_f32_16x16x32_bf16 v[48:51], v[160:163], v[168:171], v[48:51]
	v_mfma_f32_16x16x32_bf16 v[40:43], v[152:155], v[176:179], v[40:43]
	v_mfma_f32_16x16x32_bf16 v[32:35], v[160:163], v[176:179], v[32:35]
	v_mfma_f32_16x16x32_bf16 v[24:27], v[152:155], v[210:213], v[24:27]
	v_mfma_f32_16x16x32_bf16 v[16:19], v[160:163], v[210:213], v[16:19]
	v_mfma_f32_16x16x32_bf16 v[8:11], v[152:155], v[218:221], v[8:11]
	v_mfma_f32_16x16x32_bf16 v[0:3], v[160:163], v[218:221], v[0:3]
	s_setprio 0
	s_barrier
	s_cbranch_scc0 .LBB0_305
	s_and_b64 vcc, exec, s[24:25]
	s_cbranch_vccz .LBB0_309
	s_barrier
	s_lshl_b32 s40, s94, 8
	s_cmp_lt_i32 s93, 2
	s_mov_b64 s[10:11], -1
	s_cbranch_scc0 .LBB0_310
